# diff attn QK block: drop negm copy movs, counted lgkmcnt, DMA in MFMA gaps
# speedup vs baseline: 1.0225x; 1.0225x over previous
; #define LAS __attribute__((address_space(3)))
; #define MFMA32(a, b, c) __builtin_amdgcn_mfma_f32_32x32x16_bf16((a), (b), (c), 0, 0, 0)
; #define ATT_SB() __builtin_amdgcn_sched_barrier(0)
; template <bool FOX> ...
;     ...
;             bf16x8 kf[8];
; #pragma unroll
;             for (int s = 0; s < 4; ++s) { kf[2 * s] = *(LAS const bf16x8*)(kb + koff[s]); kf[2 * s + 1] = *(LAS const bf16x8*)(kb + koff[s] + 8192); }
;             if (have_next2) ATT_DMA(tn2, (buf + 2) & 3);
;             if (FOX) {
;                 LAS const float* ck = (LAS const float*)(lds + ATT_CK + buf * 512) + 64 * stream;
;                 ckfirst = ck[0] * LOG2E;
;                 ck += 8 * hi;
;                 const float cqm = cq2 - mref;
; #pragma unroll
;                 for (int rr = 0; rr < 2; ++rr) {
;                     const f32x4 a0 = *(LAS const f32x4*)(ck + 16 * rr), a1 = *(LAS const f32x4*)(ck + 16 * rr + 4), b0 = *(LAS const f32x4*)(ck + 32 + 16 * rr), b1 = *(LAS const f32x4*)(ck + 32 + 16 * rr + 4);
; #pragma unroll
;                     for (int e = 0; e < 4; ++e) { s0[8 * rr + e] = cqm - LOG2E * a0[e]; s0[8 * rr + 4 + e] = cqm - LOG2E * a1[e]; s1[8 * rr + e] = cqm - LOG2E * b0[e]; s1[8 * rr + 4 + e] = cqm - LOG2E * b1[e]; }
;                 }
;                 ATT_SB();
;                 s0 = MFMA32(kf[0], qf[0], s0); s1 = MFMA32(kf[1], qf[0], s1);
;             } else {
;                 ATT_SB();
;                 s0 = MFMA32(kf[0], qf[0], negm); s1 = MFMA32(kf[1], qf[0], negm);
;             }
; #pragma unroll
;             for (int s = 1; s < 4; ++s) { s0 = MFMA32(kf[2 * s], qf[s], s0); s1 = MFMA32(kf[2 * s + 1], qf[s], s1); }
.LBB0_566:
	s_andn2_b64 vcc, exec, s[14:15]
	s_add_i32 s14, s25, 0
	s_cbranch_vccnz .LBB0_570
	v_add_u32_e32 v17, s14, v238
	ds_read_b128 v[112:115], v17
	ds_read_b128 v[172:175], v17 offset:8192
	v_add_u32_e32 v17, s14, v239
	ds_read_b128 v[176:179], v17
	ds_read_b128 v[164:167], v17 offset:8192
	v_add_u32_e32 v17, s14, v240
	ds_read_b128 v[168:171], v17
	ds_read_b128 v[22:25], v17 offset:8192
	v_add_u32_e32 v17, s14, v241
	ds_read_b128 v[26:29], v17
	ds_read_b128 v[18:21], v17 offset:8192
	s_and_b64 vcc, exec, s[6:7]
	s_cbranch_vccnz .LBB0_569
	s_xor_b32 s15, s25, 0x10000
	s_lshl_b64 s[6:7], s[16:17], 10
	s_add_i32 s15, s24, s15
	s_add_i32 s25, s15, 0x400
	s_add_i32 s28, s15, 0x4000
	s_mov_b32 m0, s15
	v_lshl_add_u64 v[30:31], v[200:201], 0, s[6:7]
	s_waitcnt lgkmcnt(7)
	v_mfma_f32_32x32x16_bf16 v[128:143], v[112:115], v[2:5], v[96:111]
	global_load_lds_dwordx4 v[30:31], off
	s_mov_b32 m0, s25
	v_lshl_add_u64 v[30:31], v[198:199], 0, s[6:7]
	s_waitcnt lgkmcnt(5)
	v_mfma_f32_32x32x16_bf16 v[128:143], v[176:179], v[6:9], v[128:143]
	v_mfma_f32_32x32x16_bf16 v[112:127], v[172:175], v[2:5], v[96:111]
	global_load_lds_dwordx4 v[30:31], off
	s_mov_b32 m0, s28
	v_lshl_add_u64 v[30:31], v[196:197], 0, s[6:7]
	s_waitcnt lgkmcnt(3)
	v_mfma_f32_32x32x16_bf16 v[112:127], v[164:167], v[6:9], v[112:127]
	v_mfma_f32_32x32x16_bf16 v[128:143], v[168:171], v[10:13], v[128:143]
	global_load_lds_dwordx4 v[30:31], off
	v_lshl_add_u64 v[30:31], v[202:203], 0, s[6:7]
	s_add_i32 s6, s15, 0x4400
	s_mov_b32 m0, s6
	s_waitcnt lgkmcnt(1)
	v_mfma_f32_32x32x16_bf16 v[112:127], v[22:25], v[10:13], v[112:127]
	v_mfma_f32_32x32x16_bf16 v[128:143], v[26:29], v[144:147], v[128:143]
	global_load_lds_dwordx4 v[30:31], off
	s_waitcnt lgkmcnt(0)
	v_mfma_f32_32x32x16_bf16 v[112:127], v[18:21], v[144:147], v[112:127]
	s_branch .LBB0_571
.LBB0_569:
	s_waitcnt lgkmcnt(7)
	v_mfma_f32_32x32x16_bf16 v[128:143], v[112:115], v[2:5], v[96:111]
	s_waitcnt lgkmcnt(5)
	v_mfma_f32_32x32x16_bf16 v[128:143], v[176:179], v[6:9], v[128:143]
	v_mfma_f32_32x32x16_bf16 v[112:127], v[172:175], v[2:5], v[96:111]
	s_waitcnt lgkmcnt(3)
	v_mfma_f32_32x32x16_bf16 v[112:127], v[164:167], v[6:9], v[112:127]
	v_mfma_f32_32x32x16_bf16 v[128:143], v[168:171], v[10:13], v[128:143]
	s_waitcnt lgkmcnt(1)
	v_mfma_f32_32x32x16_bf16 v[112:127], v[22:25], v[10:13], v[112:127]
	v_mfma_f32_32x32x16_bf16 v[128:143], v[26:29], v[144:147], v[128:143]
	s_waitcnt lgkmcnt(0)
	v_mfma_f32_32x32x16_bf16 v[112:127], v[18:21], v[144:147], v[112:127]
	s_branch .LBB0_571
